# v23 + S5 lag-kernel table loops (both layers): two state blocks per trip, the second block's eight loads requested before the first block is reduced
# speedup vs baseline: 1.0029x; 1.0029x over previous
; __device__ __forceinline__ void ssm_build_mef(const Params& p, const Ctx& c, int l) {
;     ...
;   for (long i = c.gtid; i < 32L * 2 * 32 * 256; i += c.nthr) { const int hp = (int)(i & 15), h = (int)((i >> 4) & 15), j = (int)((i >> 8) & 31), gd = (int)(i >> 13), d = gd & 1, g = gd >> 1;
;     const size_t ci = ((size_t)((l * 2 + d) * 32 + g) * 16 + h) * 64; const float2* pw = PW + ((size_t)gd * 33 + j) * 64; const float2* bb = BB + (size_t)gd * 64 * 16 + hp; float a = 0.f;
;     for (int pp = 0; pp < 64; ++pp) { const float cr = p.ssm_c_re[ci + pp], cim = p.ssm_c_im[ci + pp]; const float2 b = bb[pp * 16], w = pw[pp];
;       const float wr = cr * b.x - cim * b.y, wi = cr * b.y + cim * b.x; a += wr * w.x - wi * w.y; }
;     MK[i] = a; }
.LBB0_178:
	v_lshl_add_u64 v[28:29], v[18:19], 0, s[36:37]
	v_lshl_add_u64 v[32:33], s[10:11], 0, v[12:13]
	v_lshl_add_u64 v[30:31], v[16:17], 0, s[36:37]
	global_load_dwordx4 v[20:23], v[28:29], off
	global_load_dwordx4 v[24:27], v[30:31], off
	v_add_co_u32_e32 v28, vcc, 0xabcc000, v32
	v_lshl_add_u64 v[34:35], s[10:11], 0, v[14:15]
	s_nop 0
	v_addc_co_u32_e32 v29, vcc, 0, v33, vcc
	v_add_co_u32_e32 v38, vcc, 0xa9bc000, v34
	global_load_dwordx2 v[40:41], v[28:29], off
	global_load_dwordx2 v[42:43], v[28:29], off offset:128
	global_load_dwordx2 v[44:45], v[28:29], off offset:256
	global_load_dwordx2 v[46:47], v[28:29], off offset:384
	v_addc_co_u32_e32 v39, vcc, 0, v35, vcc
	v_lshl_add_u64 v[36:37], v[34:35], 0, s[20:21]
	global_load_dwordx4 v[28:31], v[38:39], off
	global_load_dwordx4 v[32:35], v[36:37], off offset:16
	s_add_u32 s36, s36, 16
	s_addc_u32 s37, s37, 0
	v_lshl_add_u64 v[12:13], v[12:13], 0, s[24:25]
	v_lshl_add_u64 v[14:15], v[14:15], 0, 32
	s_cmpk_eq_i32 s36, 0x100
	v_lshl_add_u64 v[158:159], v[18:19], 0, s[36:37]
	v_lshl_add_u64 v[162:163], s[10:11], 0, v[12:13]
	v_lshl_add_u64 v[160:161], v[16:17], 0, s[36:37]
	global_load_dwordx4 v[150:153], v[158:159], off
	global_load_dwordx4 v[154:157], v[160:161], off
	v_add_co_u32_e32 v158, vcc, 0xabcc000, v162
	v_lshl_add_u64 v[164:165], s[10:11], 0, v[14:15]
	s_nop 0
	v_addc_co_u32_e32 v159, vcc, 0, v163, vcc
	v_add_co_u32_e32 v168, vcc, 0xa9bc000, v164
	global_load_dwordx2 v[170:171], v[158:159], off
	global_load_dwordx2 v[172:173], v[158:159], off offset:128
	global_load_dwordx2 v[174:175], v[158:159], off offset:256
	global_load_dwordx2 v[176:177], v[158:159], off offset:384
	v_addc_co_u32_e32 v169, vcc, 0, v165, vcc
	v_lshl_add_u64 v[166:167], v[164:165], 0, s[20:21]
	global_load_dwordx4 v[158:161], v[168:169], off
	global_load_dwordx4 v[162:165], v[166:167], off offset:16
	s_add_u32 s36, s36, 16
	s_addc_u32 s37, s37, 0
	v_lshl_add_u64 v[12:13], v[12:13], 0, s[24:25]
	v_lshl_add_u64 v[14:15], v[14:15], 0, 32
	s_cmpk_eq_i32 s36, 0x100
	s_waitcnt vmcnt(15)
	v_mov_b32_e32 v36, v21
	s_waitcnt vmcnt(14)
	v_mov_b32_e32 v50, v27
	v_mov_b32_e32 v38, v23
	v_mov_b32_e32 v48, v23
	s_waitcnt vmcnt(13)
	v_pk_mul_f32 v[52:53], v[24:25], v[40:41] op_sel:[0,1] op_sel_hi:[0,0]
	s_waitcnt vmcnt(12)
	v_pk_mul_f32 v[24:25], v[24:25], v[42:43] op_sel:[1,1] op_sel_hi:[1,0]
	v_pk_fma_f32 v[54:55], v[20:21], v[40:41], v[52:53] neg_lo:[0,0,1] neg_hi:[0,0,1]
	v_pk_fma_f32 v[40:41], v[20:21], v[40:41], v[52:53] op_sel_hi:[0,1,1]
	s_waitcnt vmcnt(11)
	v_pk_mul_f32 v[26:27], v[26:27], v[44:45] op_sel:[0,1] op_sel_hi:[0,0]
	v_pk_fma_f32 v[36:37], v[36:37], v[42:43], v[24:25] neg_lo:[0,0,1] neg_hi:[0,0,1]
	v_pk_fma_f32 v[20:21], v[20:21], v[42:43], v[24:25] op_sel:[1,0,0]
	v_mov_b32_e32 v55, v41
	s_waitcnt vmcnt(10)
	v_pk_mul_f32 v[50:51], v[50:51], v[46:47] op_sel:[0,1] op_sel_hi:[0,0]
	v_pk_fma_f32 v[24:25], v[22:23], v[44:45], v[26:27] neg_lo:[0,0,1] neg_hi:[0,0,1]
	v_pk_fma_f32 v[22:23], v[22:23], v[44:45], v[26:27] op_sel_hi:[0,1,1]
	v_mov_b32_e32 v37, v21
	s_waitcnt vmcnt(9)
	v_pk_mul_f32 v[20:21], v[28:29], v[54:55]
	v_pk_fma_f32 v[26:27], v[38:39], v[46:47], v[50:51] neg_lo:[0,0,1] neg_hi:[0,0,1]
	v_pk_fma_f32 v[38:39], v[48:49], v[46:47], v[50:51] op_sel_hi:[0,1,1]
	v_mov_b32_e32 v25, v23
	v_pk_mul_f32 v[22:23], v[30:31], v[36:37]
	v_sub_f32_e32 v20, v20, v21
	v_mov_b32_e32 v27, v39
	s_waitcnt vmcnt(8)
	v_pk_mul_f32 v[24:25], v[32:33], v[24:25]
	v_sub_f32_e32 v21, v22, v23
	v_add_f32_e32 v6, v6, v20
	v_pk_mul_f32 v[26:27], v[34:35], v[26:27]
	v_sub_f32_e32 v22, v24, v25
	v_add_f32_e32 v6, v6, v21
	v_sub_f32_e32 v23, v26, v27
	v_add_f32_e32 v6, v6, v22
	v_add_f32_e32 v6, v6, v23
	s_waitcnt vmcnt(7)
	v_mov_b32_e32 v166, v151
	s_waitcnt vmcnt(6)
	v_mov_b32_e32 v180, v157
	v_mov_b32_e32 v168, v153
	v_mov_b32_e32 v178, v153
	s_waitcnt vmcnt(5)
	v_pk_mul_f32 v[182:183], v[154:155], v[170:171] op_sel:[0,1] op_sel_hi:[0,0]
	s_waitcnt vmcnt(4)
	v_pk_mul_f32 v[154:155], v[154:155], v[172:173] op_sel:[1,1] op_sel_hi:[1,0]
	v_pk_fma_f32 v[184:185], v[150:151], v[170:171], v[182:183] neg_lo:[0,0,1] neg_hi:[0,0,1]
	v_pk_fma_f32 v[170:171], v[150:151], v[170:171], v[182:183] op_sel_hi:[0,1,1]
	s_waitcnt vmcnt(3)
	v_pk_mul_f32 v[156:157], v[156:157], v[174:175] op_sel:[0,1] op_sel_hi:[0,0]
	v_pk_fma_f32 v[166:167], v[166:167], v[172:173], v[154:155] neg_lo:[0,0,1] neg_hi:[0,0,1]
	v_pk_fma_f32 v[150:151], v[150:151], v[172:173], v[154:155] op_sel:[1,0,0]
	v_mov_b32_e32 v185, v171
	s_waitcnt vmcnt(2)
	v_pk_mul_f32 v[180:181], v[180:181], v[176:177] op_sel:[0,1] op_sel_hi:[0,0]
	v_pk_fma_f32 v[154:155], v[152:153], v[174:175], v[156:157] neg_lo:[0,0,1] neg_hi:[0,0,1]
	v_pk_fma_f32 v[152:153], v[152:153], v[174:175], v[156:157] op_sel_hi:[0,1,1]
	v_mov_b32_e32 v167, v151
	s_waitcnt vmcnt(1)
	v_pk_mul_f32 v[150:151], v[158:159], v[184:185]
	v_pk_fma_f32 v[156:157], v[168:169], v[176:177], v[180:181] neg_lo:[0,0,1] neg_hi:[0,0,1]
	v_pk_fma_f32 v[168:169], v[178:179], v[176:177], v[180:181] op_sel_hi:[0,1,1]
	v_mov_b32_e32 v155, v153
	v_pk_mul_f32 v[152:153], v[160:161], v[166:167]
	v_sub_f32_e32 v150, v150, v151
	v_mov_b32_e32 v157, v169
	s_waitcnt vmcnt(0)
	v_pk_mul_f32 v[154:155], v[162:163], v[154:155]
	v_sub_f32_e32 v151, v152, v153
	v_add_f32_e32 v6, v6, v150
	v_pk_mul_f32 v[156:157], v[164:165], v[156:157]
	v_sub_f32_e32 v152, v154, v155
	v_add_f32_e32 v6, v6, v151
	v_sub_f32_e32 v153, v156, v157
	v_add_f32_e32 v6, v6, v152
	v_add_f32_e32 v6, v6, v153
	s_cbranch_scc0 .LBB0_178
	v_readlane_b32 s22, v250, 2
	v_readlane_b32 s23, v250, 3
	v_lshl_add_u64 v[12:13], v[10:11], 2, s[14:15]
	v_lshl_add_u64 v[8:9], v[8:9], 0, s[18:19]
	v_lshl_add_u64 v[10:11], v[10:11], 0, s[22:23]
	v_cmp_lt_i64_e32 vcc, s[34:35], v[10:11]
	s_or_b64 s[16:17], vcc, s[16:17]
	global_store_dword v[12:13], v6, off
	s_andn2_b64 exec, exec, s[16:17]
	s_cbranch_execnz .LBB0_177
	s_or_b64 exec, exec, s[16:17]
	s_add_u32 s14, s10, 0xa9bc000
	s_addc_u32 s15, s11, 0
	s_add_u32 s4, s10, 0xabcc000
	s_addc_u32 s5, s11, 0
	s_add_u32 s6, s10, 0xc8cc000
	s_addc_u32 s7, s11, 0
	s_lshl_b64 s[0:1], s[12:13], 12
	v_lshl_add_u64 v[4:5], v[4:5], 3, s[0:1]
	s_lshl_b64 s[16:17], s[30:31], 12
	s_mov_b64 s[12:13], 0
	s_movk_i32 s0, 0x80
	v_mov_b32_e32 v7, 0
	s_mov_b64 s[18:19], 0x7ffff
	v_mov_b64_e32 v[8:9], v[0:1]

; __device__ __forceinline__ void ssm_build_mef(const Params& p, const Ctx& c, int l) {
;     ...
;   for (long i = c.gtid; i < 32L * 2 * 32 * 256; i += c.nthr) { const int hp = (int)(i & 15), h = (int)((i >> 4) & 15), j = (int)((i >> 8) & 31), gd = (int)(i >> 13), d = gd & 1, g = gd >> 1;
;     const size_t ci = ((size_t)((l * 2 + d) * 32 + g) * 16 + h) * 64; const float2* pw = PW + ((size_t)gd * 33 + j) * 64; const float2* bb = BB + (size_t)gd * 64 * 16 + hp; float a = 0.f;
;     for (int pp = 0; pp < 64; ++pp) { const float cr = p.ssm_c_re[ci + pp], cim = p.ssm_c_im[ci + pp]; const float2 b = bb[pp * 16], w = pw[pp];
;       const float wr = cr * b.x - cim * b.y, wi = cr * b.y + cim * b.x; a += wr * w.x - wi * w.y; }
;     MK[i] = a; }
.LBB0_967:
	v_lshl_add_u64 v[16:17], v[14:15], 0, s[62:63]
	global_load_dwordx4 v[22:25], v[16:17], off
	v_lshl_add_u64 v[16:17], v[12:13], 0, s[62:63]
	global_load_dwordx4 v[26:29], v[16:17], off
	v_lshl_add_u64 v[16:17], s[54:55], 0, v[8:9]
	v_add_co_u32_e32 v16, vcc, 0xac4c000, v16
	v_lshl_add_u64 v[30:31], s[54:55], 0, v[10:11]
	s_nop 0
	v_addc_co_u32_e32 v17, vcc, 0, v17, vcc
	global_load_dwordx2 v[38:39], v[16:17], off
	global_load_dwordx2 v[60:61], v[16:17], off offset:128
	global_load_dwordx2 v[62:63], v[16:17], off offset:256
	global_load_dwordx2 v[64:65], v[16:17], off offset:384
	s_mov_b64 s[0:1], 0xaac4000
	v_lshl_add_u64 v[34:35], v[30:31], 0, s[0:1]
	v_add_co_u32_e32 v30, vcc, 0xaac4000, v30
	s_add_u32 s62, s62, 16
	s_nop 0
	v_addc_co_u32_e32 v31, vcc, 0, v31, vcc
	global_load_dwordx4 v[30:33], v[30:31], off
	s_nop 0
	global_load_dwordx4 v[34:37], v[34:35], off offset:16
	s_mov_b64 s[0:1], 0x200
	s_addc_u32 s63, s63, 0
	v_lshl_add_u64 v[8:9], v[8:9], 0, s[0:1]
	v_lshl_add_u64 v[10:11], v[10:11], 0, 32
	s_cmpk_eq_i32 s62, 0x100
	v_lshl_add_u64 v[86:87], v[14:15], 0, s[62:63]
	global_load_dwordx4 v[92:95], v[86:87], off
	v_lshl_add_u64 v[86:87], v[12:13], 0, s[62:63]
	global_load_dwordx4 v[96:99], v[86:87], off
	v_lshl_add_u64 v[86:87], s[54:55], 0, v[8:9]
	v_add_co_u32_e32 v86, vcc, 0xac4c000, v86
	v_lshl_add_u64 v[100:101], s[54:55], 0, v[10:11]
	s_nop 0
	v_addc_co_u32_e32 v87, vcc, 0, v87, vcc
	global_load_dwordx2 v[108:109], v[86:87], off
	global_load_dwordx2 v[130:131], v[86:87], off offset:128
	global_load_dwordx2 v[132:133], v[86:87], off offset:256
	global_load_dwordx2 v[134:135], v[86:87], off offset:384
	s_mov_b64 s[0:1], 0xaac4000
	v_lshl_add_u64 v[104:105], v[100:101], 0, s[0:1]
	v_add_co_u32_e32 v100, vcc, 0xaac4000, v100
	s_add_u32 s62, s62, 16
	s_nop 0
	v_addc_co_u32_e32 v101, vcc, 0, v101, vcc
	global_load_dwordx4 v[100:103], v[100:101], off
	s_nop 0
	global_load_dwordx4 v[104:107], v[104:105], off offset:16
	s_mov_b64 s[0:1], 0x200
	s_addc_u32 s63, s63, 0
	v_lshl_add_u64 v[8:9], v[8:9], 0, s[0:1]
	v_lshl_add_u64 v[10:11], v[10:11], 0, 32
	s_cmpk_eq_i32 s62, 0x100
	s_waitcnt vmcnt(13)
	v_pk_mul_f32 v[40:41], v[26:27], v[38:39] op_sel:[0,1] op_sel_hi:[0,0]
	v_pk_fma_f32 v[42:43], v[22:23], v[38:39], v[40:41] neg_lo:[0,0,1] neg_hi:[0,0,1]
	v_pk_fma_f32 v[38:39], v[22:23], v[38:39], v[40:41] op_sel_hi:[0,1,1]
	v_mov_b32_e32 v43, v39
	v_mov_b32_e32 v38, v23
	s_waitcnt vmcnt(9)
	v_pk_mul_f32 v[30:31], v[30:31], v[42:43]
	s_nop 0
	v_sub_f32_e32 v30, v30, v31
	v_add_f32_e32 v1, v1, v30
	s_waitcnt vmcnt(8)
	v_mov_b64_e32 v[30:31], v[60:61]
	v_pk_mul_f32 v[26:27], v[26:27], v[30:31] op_sel:[1,1] op_sel_hi:[1,0]
	s_nop 0
	v_pk_fma_f32 v[38:39], v[38:39], v[30:31], v[26:27] neg_lo:[0,0,1] neg_hi:[0,0,1]
	v_pk_fma_f32 v[22:23], v[22:23], v[30:31], v[26:27] op_sel:[1,0,0]
	s_nop 0
	v_mov_b32_e32 v39, v23
	v_pk_mul_f32 v[22:23], v[32:33], v[38:39]
	s_nop 0
	v_sub_f32_e32 v22, v22, v23
	v_add_f32_e32 v1, v1, v22
	s_waitcnt vmcnt(8)
	v_mov_b64_e32 v[22:23], v[62:63]
	v_pk_mul_f32 v[26:27], v[28:29], v[22:23] op_sel:[0,1] op_sel_hi:[0,0]
	v_mov_b64_e32 v[16:17], v[64:65]
	v_pk_fma_f32 v[30:31], v[24:25], v[22:23], v[26:27] neg_lo:[0,0,1] neg_hi:[0,0,1]
	v_pk_fma_f32 v[22:23], v[24:25], v[22:23], v[26:27] op_sel_hi:[0,1,1]
	v_mov_b32_e32 v31, v23
	v_pk_mul_f32 v[22:23], v[34:35], v[30:31]
	v_mov_b32_e32 v26, v29
	v_sub_f32_e32 v22, v22, v23
	v_add_f32_e32 v1, v1, v22
	v_mov_b32_e32 v22, v25
	v_mov_b32_e32 v24, v25
	s_waitcnt vmcnt(8)
	v_pk_mul_f32 v[26:27], v[26:27], v[16:17] op_sel:[0,1] op_sel_hi:[0,0]
	v_pk_fma_f32 v[22:23], v[22:23], v[16:17], v[26:27] neg_lo:[0,0,1] neg_hi:[0,0,1]
	v_pk_fma_f32 v[16:17], v[24:25], v[16:17], v[26:27] op_sel_hi:[0,1,1]
	v_mov_b32_e32 v23, v17
	v_pk_mul_f32 v[16:17], v[36:37], v[22:23]
	s_nop 0
	v_sub_f32_e32 v16, v16, v17
	v_add_f32_e32 v1, v1, v16
	s_waitcnt vmcnt(5)
	v_pk_mul_f32 v[110:111], v[96:97], v[108:109] op_sel:[0,1] op_sel_hi:[0,0]
	v_pk_fma_f32 v[112:113], v[92:93], v[108:109], v[110:111] neg_lo:[0,0,1] neg_hi:[0,0,1]
	v_pk_fma_f32 v[108:109], v[92:93], v[108:109], v[110:111] op_sel_hi:[0,1,1]
	v_mov_b32_e32 v113, v109
	v_mov_b32_e32 v108, v93
	s_waitcnt vmcnt(1)
	v_pk_mul_f32 v[100:101], v[100:101], v[112:113]
	s_nop 0
	v_sub_f32_e32 v100, v100, v101
	v_add_f32_e32 v1, v1, v100
	s_waitcnt vmcnt(0)
	v_mov_b64_e32 v[100:101], v[130:131]
	v_pk_mul_f32 v[96:97], v[96:97], v[100:101] op_sel:[1,1] op_sel_hi:[1,0]
	s_nop 0
	v_pk_fma_f32 v[108:109], v[108:109], v[100:101], v[96:97] neg_lo:[0,0,1] neg_hi:[0,0,1]
	v_pk_fma_f32 v[92:93], v[92:93], v[100:101], v[96:97] op_sel:[1,0,0]
	s_nop 0
	v_mov_b32_e32 v109, v93
	v_pk_mul_f32 v[92:93], v[102:103], v[108:109]
	s_nop 0
	v_sub_f32_e32 v92, v92, v93
	v_add_f32_e32 v1, v1, v92
	s_waitcnt vmcnt(0)
	v_mov_b64_e32 v[92:93], v[132:133]
	v_pk_mul_f32 v[96:97], v[98:99], v[92:93] op_sel:[0,1] op_sel_hi:[0,0]
	v_mov_b64_e32 v[86:87], v[134:135]
	v_pk_fma_f32 v[100:101], v[94:95], v[92:93], v[96:97] neg_lo:[0,0,1] neg_hi:[0,0,1]
	v_pk_fma_f32 v[92:93], v[94:95], v[92:93], v[96:97] op_sel_hi:[0,1,1]
	v_mov_b32_e32 v101, v93
	v_pk_mul_f32 v[92:93], v[104:105], v[100:101]
	v_mov_b32_e32 v96, v99
	v_sub_f32_e32 v92, v92, v93
	v_add_f32_e32 v1, v1, v92
	v_mov_b32_e32 v92, v95
	v_mov_b32_e32 v94, v95
	s_waitcnt vmcnt(0)
	v_pk_mul_f32 v[96:97], v[96:97], v[86:87] op_sel:[0,1] op_sel_hi:[0,0]
	v_pk_fma_f32 v[92:93], v[92:93], v[86:87], v[96:97] neg_lo:[0,0,1] neg_hi:[0,0,1]
	v_pk_fma_f32 v[86:87], v[94:95], v[86:87], v[96:97] op_sel_hi:[0,1,1]
	v_mov_b32_e32 v93, v87
	v_pk_mul_f32 v[86:87], v[106:107], v[92:93]
	s_nop 0
	v_sub_f32_e32 v86, v86, v87
	v_add_f32_e32 v1, v1, v86
	s_cbranch_scc0 .LBB0_967
	v_lshl_add_u64 v[8:9], v[6:7], 2, s[56:57]
	v_lshl_add_u64 v[6:7], v[6:7], 0, s[22:23]
	v_readlane_b32 s0, v250, 5
	v_cmp_lt_i64_e32 vcc, s[70:71], v[6:7]
	v_readlane_b32 s1, v250, 6
	s_or_b64 s[60:61], vcc, s[60:61]
	global_store_dword v[8:9], v1, off
	v_lshl_add_u64 v[4:5], v[4:5], 0, s[0:1]
	s_andn2_b64 exec, exec, s[60:61]
	s_cbranch_execnz .LBB0_966
	s_or_b64 exec, exec, s[60:61]
	s_add_u32 s56, s54, 0xaac4000
	s_addc_u32 s57, s55, 0
	s_add_u32 s12, s54, 0xac4c000
	s_addc_u32 s13, s55, 0
	s_add_u32 s14, s54, 0xc8cc000
	s_addc_u32 s15, s55, 0
	s_lshl_b64 s[0:1], s[58:59], 12
	v_lshl_add_u64 v[22:23], v[2:3], 3, s[0:1]
	s_mov_b64 s[58:59], 0
	v_mov_b64_e32 v[24:25], v[18:19]
